# P1 K loop: per-phase s_setprio flips replaced by one static raise for waves 0-3, with the loop head and all later code kept at their byte phase (the earlier uncompensated test was confounded by placem
# speedup vs baseline: 1.0107x; 1.0055x over previous
; #define PG8_STAGE(bufoff, gbase, voff) do { _Pragma("unroll") for (int _i = 0; _i < 2; ++_i) \
;         __builtin_amdgcn_global_load_lds((const unsigned*)((const char*)(gbase) + (voff)[_i]), (LAS unsigned*)(lds + (bufoff) + ldsw + _i * 8192), 16, 0, 0); } while (0)
; #define PG8_LDA(dst, b, h) do { _Pragma("unroll") for (int m = 0; m < 4; ++m) _Pragma("unroll") for (int k = 0; k < 2; ++k) dst[m][k] = *(const LAS bf16x8*)(lds + PG8_SA(b, h) + aoff + m * 2048 + k * 1024); } while (0)
; #define PG8_LDB(dst, b, h) do { _Pragma("unroll") for (int n = 0; n < 2; ++n) _Pragma("unroll") for (int k = 0; k < 2; ++k) dst[n][k] = *(const LAS bf16x8*)(lds + PG8_SB(b, h) + boff + n * 2048 + k * 1024); } while (0)
; #define PG8_WAIT_L(n) asm volatile("s_waitcnt lgkmcnt(" #n ")" ::: "memory")
; #define PG8_BAR __builtin_amdgcn_s_barrier()
; #define PG8_SCHED __builtin_amdgcn_sched_barrier(0)
; template <class Epi, class Sched>
; __device__ __forceinline__ void gemm_phase(LAS unsigned char* lds, const Gemm g, const Sched& S, const Epi& E) {
;     ...
;     for (;;) {
;         const bool has_next = S.next(ui + 1, nxt);
;         const char* nA = has_next ? (const char*)g.A + (size_t)nxt.pm * tstepA + (size_t)nxt.koffA * 2 : cA; const char* nB = has_next ? (const char*)g.Bt + (size_t)nxt.pn * tstepB + (size_t)nxt.koffB * 2 : cB;
; #pragma clang loop unroll(disable)
;         for (int t = 0; t < nt; t += 2) {
;             const bool last = (t == nt - 2);
;             const char* a1 = cA + (size_t)(t + 1) * kstep;
;             const char* a2 = last ? nA : cA + (size_t)(t + 2) * kstep; const char* b2 = last ? nB : cB + (size_t)(t + 2) * kstep;
;             const char* a3 = a2 + kstep; const char* b3 = b2 + kstep;
;             PG8_LDB(B0, 0, 0); PG8_SCHED; PG8_LDA(At, 0, 0); PG8_STAGE(PG8_SA(1, 1), a1 + hstepA, voffA);
;             PG8_WAIT_L(8); PG8_BAR; PG8_WAIT_L(0); PG8_MMA(0, 0, At, B0); PG8_BAR; PG8_SCHED;
;     ...
;         if (!has_next) break;
; #pragma unroll
;         for (int a = 0; a < 2; ++a)
; #pragma unroll
;             for (int b = 0; b < 2; ++b)
; #pragma unroll
;                 for (int m = 0; m < 4; ++m)
; #pragma unroll
;                     for (int n = 0; n < 2; ++n) acc[a][b][m][n] = (f32x4){0.f, 0.f, 0.f, 0.f};
;         cur = nxt; cA = nA; cB = nB; ++ui;
.LBB0_120:
	s_ashr_i32 s13, s12, 31
	v_cmp_lt_i64_e32 vcc, s[4:5], v[140:141]
	s_lshl_b64 s[4:5], s[12:13], 20
	s_add_u32 s14, s46, s4
	s_addc_u32 s15, s47, s5
	s_and_b64 s[4:5], vcc, exec
	s_cselect_b32 s4, s15, s21
	s_cselect_b32 s5, s14, s20
	s_ashr_i32 s11, s10, 31
	s_lshl_b64 s[18:19], s[10:11], 20
	s_add_u32 s18, s90, s18
	s_addc_u32 s19, s91, s19
	s_and_b64 s[26:27], vcc, exec
	s_cselect_b32 s11, s19, s25
	s_cselect_b32 s13, s18, s24
	s_add_u32 s20, s20, 0x80080
	s_addc_u32 s21, s21, 0
	s_add_u32 s62, s24, 0x100
	v_mov_b32_e32 v0, 0
	s_addc_u32 s63, s25, 0
	s_mov_b32 s64, -2
	v_mov_b32_e32 v1, v0
	v_mov_b32_e32 v2, v0
	v_mov_b32_e32 v3, v0
	v_mov_b32_e32 v4, v0
	v_mov_b32_e32 v5, v0
	v_mov_b32_e32 v6, v0
	v_mov_b32_e32 v7, v0
	v_mov_b32_e32 v8, v0
	v_mov_b32_e32 v9, v0
	v_mov_b32_e32 v10, v0
	v_mov_b32_e32 v11, v0
	v_mov_b32_e32 v12, v0
	v_mov_b32_e32 v13, v0
	v_mov_b32_e32 v14, v0
	v_mov_b32_e32 v15, v0
	v_mov_b32_e32 v16, v0
	v_mov_b32_e32 v17, v0
	v_mov_b32_e32 v18, v0
	v_mov_b32_e32 v19, v0
	v_mov_b32_e32 v20, v0
	v_mov_b32_e32 v21, v0
	v_mov_b32_e32 v22, v0
	v_mov_b32_e32 v23, v0
	v_mov_b32_e32 v24, v0
	v_mov_b32_e32 v25, v0
	v_mov_b32_e32 v26, v0
	v_mov_b32_e32 v27, v0
	v_mov_b32_e32 v28, v0
	v_mov_b32_e32 v29, v0
	v_mov_b32_e32 v30, v0
	v_mov_b32_e32 v31, v0
	v_mov_b32_e32 v48, v0
	v_mov_b32_e32 v49, v0
	v_mov_b32_e32 v50, v0
	v_mov_b32_e32 v51, v0
	v_mov_b32_e32 v52, v0
	v_mov_b32_e32 v53, v0
	v_mov_b32_e32 v54, v0
	v_mov_b32_e32 v55, v0
	v_mov_b32_e32 v64, v0
	v_mov_b32_e32 v65, v0
	v_mov_b32_e32 v66, v0
	v_mov_b32_e32 v67, v0
	v_mov_b32_e32 v72, v0
	v_mov_b32_e32 v73, v0
	v_mov_b32_e32 v74, v0
	v_mov_b32_e32 v75, v0
	v_mov_b32_e32 v80, v0
	v_mov_b32_e32 v81, v0
	v_mov_b32_e32 v82, v0
	v_mov_b32_e32 v83, v0
	v_mov_b32_e32 v84, v0
	v_mov_b32_e32 v85, v0
	v_mov_b32_e32 v86, v0
	v_mov_b32_e32 v87, v0
	v_mov_b32_e32 v88, v0
	v_mov_b32_e32 v89, v0
	v_mov_b32_e32 v90, v0
	v_mov_b32_e32 v91, v0
	v_mov_b32_e32 v92, v0
	v_mov_b32_e32 v93, v0
	v_mov_b32_e32 v94, v0
	v_mov_b32_e32 v95, v0
	v_mov_b32_e32 v32, v0
	v_mov_b32_e32 v33, v0
	v_mov_b32_e32 v34, v0
	v_mov_b32_e32 v35, v0
	v_mov_b32_e32 v36, v0
	v_mov_b32_e32 v37, v0
	v_mov_b32_e32 v38, v0
	v_mov_b32_e32 v39, v0
	v_mov_b32_e32 v40, v0
	v_mov_b32_e32 v41, v0
	v_mov_b32_e32 v42, v0
	v_mov_b32_e32 v43, v0
	v_mov_b32_e32 v44, v0
	v_mov_b32_e32 v45, v0
	v_mov_b32_e32 v46, v0
	v_mov_b32_e32 v47, v0
	v_mov_b32_e32 v56, v0
	v_mov_b32_e32 v57, v0
	v_mov_b32_e32 v58, v0
	v_mov_b32_e32 v59, v0
	v_mov_b32_e32 v60, v0
	v_mov_b32_e32 v61, v0
	v_mov_b32_e32 v62, v0
	v_mov_b32_e32 v63, v0
	v_mov_b32_e32 v68, v0
	v_mov_b32_e32 v69, v0
	v_mov_b32_e32 v70, v0
	v_mov_b32_e32 v71, v0
	v_mov_b32_e32 v76, v0
	v_mov_b32_e32 v77, v0
	v_mov_b32_e32 v78, v0
	v_mov_b32_e32 v79, v0
	v_mov_b32_e32 v96, v0
	v_mov_b32_e32 v97, v0
	v_mov_b32_e32 v98, v0
	v_mov_b32_e32 v99, v0
	v_mov_b32_e32 v100, v0
	v_mov_b32_e32 v101, v0
	v_mov_b32_e32 v102, v0
	v_mov_b32_e32 v103, v0
	v_mov_b32_e32 v104, v0
	v_mov_b32_e32 v105, v0
	v_mov_b32_e32 v106, v0
	v_mov_b32_e32 v107, v0
	v_mov_b32_e32 v108, v0
	v_mov_b32_e32 v109, v0
	v_mov_b32_e32 v110, v0
	v_mov_b32_e32 v111, v0
	v_mov_b32_e32 v112, v0
	v_mov_b32_e32 v113, v0
	v_mov_b32_e32 v114, v0
	v_mov_b32_e32 v115, v0
	v_mov_b32_e32 v116, v0
	v_mov_b32_e32 v117, v0
	v_mov_b32_e32 v118, v0
	v_mov_b32_e32 v119, v0
	v_mov_b32_e32 v120, v0
	v_mov_b32_e32 v121, v0
	v_mov_b32_e32 v122, v0
	v_mov_b32_e32 v123, v0
	v_mov_b32_e32 v124, v0
	v_mov_b32_e32 v125, v0
	v_mov_b32_e32 v126, v0
	v_mov_b32_e32 v127, v0
	s_nop 0
	s_nop 0
	s_nop 0
	s_nop 0
	s_nop 0
	s_nop 0
	s_nop 0
	s_nop 0
	s_nop 0
	s_nop 0
	s_nop 0
	s_nop 0
	s_nop 0
	s_nop 0
	s_nop 0
	s_nop 0
	s_nop 0
	s_nop 0
	s_nop 0
	s_nop 0
	s_nop 0
	s_nop 0
	s_nop 0
	s_nop 0
	s_nop 0
	s_nop 0
	s_nop 0
	s_nop 0
	s_nop 0
	s_nop 0
	s_nop 0
	s_nop 0
	s_nop 0
	s_nop 0
	s_nop 0
	s_nop 0
	s_nop 0
	s_nop 0
	s_nop 0
	s_nop 0
	s_nop 0
	s_nop 0
	s_nop 0
	s_nop 0
	s_nop 0
	s_nop 0
	s_nop 0
	s_nop 0
	s_nop 0
	s_nop 0
	s_nop 0
	s_nop 0
	s_nop 0
	s_nop 0
	s_nop 0
	s_nop 0
	s_nop 0
	s_nop 0
	v_readfirstlane_b32 vcc_lo, v196
	s_nop 3
	s_lshr_b32 vcc_lo, vcc_lo, 8
	s_cmp_lg_u32 vcc_lo, 0
	s_cbranch_scc1 .Lp1_prio_done
	s_setprio 1
.Lp1_prio_done:
.LBB0_121:
	ds_read_b128 v[150:153], v147
	ds_read_b128 v[154:157], v147 offset:1024
	ds_read_b128 v[158:161], v147 offset:2048
	ds_read_b128 v[162:165], v147 offset:3072
	s_add_u32 s24, s20, 0xfff80080
	s_addc_u32 s25, s21, -1
	s_cmp_eq_u32 s64, 28
	s_cselect_b32 s27, s4, s25
	s_cselect_b32 s26, s5, s24
	s_cselect_b32 s25, s11, s63
	s_cselect_b32 s24, s13, s62
	v_lshl_add_u64 v[194:195], s[20:21], 0, v[136:137]
	s_add_i32 m0, s17, 0xc000
	ds_read_b128 v[166:169], v148
	ds_read_b128 v[170:173], v148 offset:1024
	ds_read_b128 v[174:177], v148 offset:2048
	ds_read_b128 v[178:181], v148 offset:3072
	ds_read_b128 v[182:185], v148 offset:4096
	ds_read_b128 v[186:189], v148 offset:5120
	ds_read_b128 v[190:193], v148 offset:6144
	ds_read_b128 v[198:201], v148 offset:7168
	global_load_lds_dwordx4 v[194:195], off
	v_lshl_add_u64 v[194:195], s[20:21], 0, v[138:139]
	s_add_i32 m0, s17, 0xe000
	s_nop 0
	global_load_lds_dwordx4 v[194:195], off
	s_waitcnt lgkmcnt(8)
	s_barrier
; #define PG8_STAGE(bufoff, gbase, voff) do { _Pragma("unroll") for (int _i = 0; _i < 2; ++_i) \
;         __builtin_amdgcn_global_load_lds((const unsigned*)((const char*)(gbase) + (voff)[_i]), (LAS unsigned*)(lds + (bufoff) + ldsw + _i * 8192), 16, 0, 0); } while (0)
; #define PG8_LDA(dst, b, h) do { _Pragma("unroll") for (int m = 0; m < 4; ++m) _Pragma("unroll") for (int k = 0; k < 2; ++k) dst[m][k] = *(const LAS bf16x8*)(lds + PG8_SA(b, h) + aoff + m * 2048 + k * 1024); } while (0)
; #define PG8_LDB(dst, b, h) do { _Pragma("unroll") for (int n = 0; n < 2; ++n) _Pragma("unroll") for (int k = 0; k < 2; ++k) dst[n][k] = *(const LAS bf16x8*)(lds + PG8_SB(b, h) + boff + n * 2048 + k * 1024); } while (0)
; #define PG8_MMA(ai, bj, At, Bt) do { __builtin_amdgcn_s_setprio(1); _Pragma("unroll") for (int m = 0; m < 4; ++m) _Pragma("unroll") for (int n = 0; n < 2; ++n) _Pragma("unroll") for (int k = 0; k < 2; ++k) \
;         acc[ai][bj][m][n] = __builtin_amdgcn_mfma_f32_16x16x32_bf16(Bt[n][k], At[m][k], acc[ai][bj][m][n], 0, 0, 0); __builtin_amdgcn_s_setprio(0); } while (0)
; #define PG8_WAIT_V(n) asm volatile("s_waitcnt vmcnt(" #n ")" ::: "memory")
; #define PG8_WAIT_L(n) asm volatile("s_waitcnt lgkmcnt(" #n ")" ::: "memory")
; #define PG8_BAR __builtin_amdgcn_s_barrier()
; #define PG8_SCHED __builtin_amdgcn_sched_barrier(0)
; template <class Epi, class Sched>
; __device__ __forceinline__ void gemm_phase(LAS unsigned char* lds, const Gemm g, const Sched& S, const Epi& E) {
;     ...
;             PG8_WAIT_L(8); PG8_BAR; PG8_WAIT_L(0); PG8_MMA(0, 0, At, B0); PG8_BAR; PG8_SCHED;
;             PG8_LDB(B1, 0, 1); PG8_STAGE(PG8_SB(0, 0), b2, voffB);
;             PG8_BAR; PG8_WAIT_L(0); PG8_MMA(0, 1, At, B1); PG8_BAR;
;             PG8_LDA(At, 0, 1); PG8_STAGE(PG8_SA(0, 0), a2, voffA);
;             PG8_BAR; PG8_WAIT_L(0); PG8_MMA(1, 0, At, B0); PG8_BAR; PG8_SCHED;
;             PG8_STAGE(PG8_SB(0, 1), b2 + hstepB, voffB);
;             PG8_WAIT_V(6); PG8_BAR; PG8_MMA(1, 1, At, B1); PG8_BAR;
	s_waitcnt lgkmcnt(0)
	s_waitcnt lgkmcnt(0)
	v_mfma_f32_16x16x32_bf16 v[124:127], v[150:153], v[166:169], v[124:127]
	v_mfma_f32_16x16x32_bf16 v[120:123], v[158:161], v[166:169], v[120:123]
	v_mfma_f32_16x16x32_bf16 v[116:119], v[150:153], v[174:177], v[116:119]
	v_mfma_f32_16x16x32_bf16 v[112:115], v[158:161], v[174:177], v[112:115]
	v_mfma_f32_16x16x32_bf16 v[108:111], v[150:153], v[182:185], v[108:111]
	v_mfma_f32_16x16x32_bf16 v[104:107], v[158:161], v[182:185], v[104:107]
	v_mfma_f32_16x16x32_bf16 v[100:103], v[150:153], v[190:193], v[100:103]
	v_mfma_f32_16x16x32_bf16 v[96:99], v[158:161], v[190:193], v[96:99]
	v_mfma_f32_16x16x32_bf16 v[124:127], v[154:157], v[170:173], v[124:127]
	v_mfma_f32_16x16x32_bf16 v[120:123], v[162:165], v[170:173], v[120:123]
	v_mfma_f32_16x16x32_bf16 v[116:119], v[154:157], v[178:181], v[116:119]
	v_mfma_f32_16x16x32_bf16 v[112:115], v[162:165], v[178:181], v[112:115]
	v_mfma_f32_16x16x32_bf16 v[108:111], v[154:157], v[186:189], v[108:111]
	v_mfma_f32_16x16x32_bf16 v[104:107], v[162:165], v[186:189], v[104:107]
	v_mfma_f32_16x16x32_bf16 v[100:103], v[154:157], v[198:201], v[100:103]
	v_mfma_f32_16x16x32_bf16 v[96:99], v[162:165], v[198:201], v[96:99]
	s_barrier
	s_add_i32 s65, s50, s22
	v_lshl_add_u64 v[194:195], s[24:25], 0, v[130:131]
	s_mov_b32 m0, s65
	ds_read_b128 v[202:205], v149
	ds_read_b128 v[206:209], v149 offset:1024
	ds_read_b128 v[210:213], v149 offset:2048
	ds_read_b128 v[214:217], v149 offset:3072
	global_load_lds_dwordx4 v[194:195], off
	v_lshl_add_u64 v[218:219], s[24:25], 0, v[134:135]
	s_add_i32 m0, s65, 0x2000
	s_nop 0
	global_load_lds_dwordx4 v[218:219], off
	s_barrier
	s_waitcnt lgkmcnt(0)
	s_waitcnt lgkmcnt(0)
	v_mfma_f32_16x16x32_bf16 v[76:79], v[202:205], v[166:169], v[76:79]
	v_mfma_f32_16x16x32_bf16 v[68:71], v[210:213], v[166:169], v[68:71]
	v_mfma_f32_16x16x32_bf16 v[60:63], v[202:205], v[174:177], v[60:63]
	v_mfma_f32_16x16x32_bf16 v[56:59], v[210:213], v[174:177], v[56:59]
	v_mfma_f32_16x16x32_bf16 v[44:47], v[202:205], v[182:185], v[44:47]
	v_mfma_f32_16x16x32_bf16 v[40:43], v[210:213], v[182:185], v[40:43]
	v_mfma_f32_16x16x32_bf16 v[36:39], v[202:205], v[190:193], v[36:39]
	v_mfma_f32_16x16x32_bf16 v[32:35], v[210:213], v[190:193], v[32:35]
	v_mfma_f32_16x16x32_bf16 v[76:79], v[206:209], v[170:173], v[76:79]
	v_mfma_f32_16x16x32_bf16 v[68:71], v[214:217], v[170:173], v[68:71]
	v_mfma_f32_16x16x32_bf16 v[60:63], v[206:209], v[178:181], v[60:63]
	v_mfma_f32_16x16x32_bf16 v[56:59], v[214:217], v[178:181], v[56:59]
	v_mfma_f32_16x16x32_bf16 v[44:47], v[206:209], v[186:189], v[44:47]
	v_mfma_f32_16x16x32_bf16 v[40:43], v[214:217], v[186:189], v[40:43]
	v_mfma_f32_16x16x32_bf16 v[36:39], v[206:209], v[198:201], v[36:39]
	v_mfma_f32_16x16x32_bf16 v[32:35], v[214:217], v[198:201], v[32:35]
	s_mov_b32 m0, s17
	v_lshl_add_u64 v[220:221], s[26:27], 0, v[128:129]
	s_barrier
	ds_read_b128 v[166:169], v148 offset:16384
	ds_read_b128 v[170:173], v148 offset:17408
	ds_read_b128 v[174:177], v148 offset:18432
	ds_read_b128 v[178:181], v148 offset:19456
	ds_read_b128 v[182:185], v148 offset:20480
	ds_read_b128 v[186:189], v148 offset:21504
	ds_read_b128 v[190:193], v148 offset:22528
	ds_read_b128 v[198:201], v148 offset:23552
	global_load_lds_dwordx4 v[220:221], off
	v_lshl_add_u64 v[222:223], s[26:27], 0, v[132:133]
	s_mov_b32 m0, s23
	s_nop 0
	global_load_lds_dwordx4 v[222:223], off
	s_barrier
	s_waitcnt lgkmcnt(0)
	s_waitcnt lgkmcnt(0)
	v_mfma_f32_16x16x32_bf16 v[92:95], v[150:153], v[166:169], v[92:95]
	v_mfma_f32_16x16x32_bf16 v[88:91], v[158:161], v[166:169], v[88:91]
	v_mfma_f32_16x16x32_bf16 v[84:87], v[150:153], v[174:177], v[84:87]
	v_mfma_f32_16x16x32_bf16 v[80:83], v[158:161], v[174:177], v[80:83]
	v_mfma_f32_16x16x32_bf16 v[72:75], v[150:153], v[182:185], v[72:75]
	v_mfma_f32_16x16x32_bf16 v[64:67], v[158:161], v[182:185], v[64:67]
	v_mfma_f32_16x16x32_bf16 v[52:55], v[150:153], v[190:193], v[52:55]
	v_mfma_f32_16x16x32_bf16 v[48:51], v[158:161], v[190:193], v[48:51]
	v_mfma_f32_16x16x32_bf16 v[92:95], v[154:157], v[170:173], v[92:95]
	v_mfma_f32_16x16x32_bf16 v[88:91], v[162:165], v[170:173], v[88:91]
	v_mfma_f32_16x16x32_bf16 v[84:87], v[154:157], v[178:181], v[84:87]
	v_mfma_f32_16x16x32_bf16 v[80:83], v[162:165], v[178:181], v[80:83]
	v_mfma_f32_16x16x32_bf16 v[72:75], v[154:157], v[186:189], v[72:75]
	v_mfma_f32_16x16x32_bf16 v[64:67], v[162:165], v[186:189], v[64:67]
	v_mfma_f32_16x16x32_bf16 v[52:55], v[154:157], v[198:201], v[52:55]
	v_mfma_f32_16x16x32_bf16 v[48:51], v[162:165], v[198:201], v[48:51]
	s_barrier
	s_add_u32 s68, s24, 0x80000
	s_addc_u32 s69, s25, 0
	s_add_i32 s65, s51, s22
	v_lshl_add_u64 v[150:151], s[68:69], 0, v[130:131]
	s_mov_b32 m0, s65
	s_nop 0
	global_load_lds_dwordx4 v[150:151], off
	v_lshl_add_u64 v[150:151], s[68:69], 0, v[134:135]
	s_add_i32 m0, s65, 0x2000
	s_nop 0
	global_load_lds_dwordx4 v[150:151], off
	s_waitcnt vmcnt(6)
	s_barrier
	v_mfma_f32_16x16x32_bf16 v[28:31], v[202:205], v[166:169], v[28:31]
	v_mfma_f32_16x16x32_bf16 v[24:27], v[210:213], v[166:169], v[24:27]
	v_mfma_f32_16x16x32_bf16 v[20:23], v[202:205], v[174:177], v[20:23]
	v_mfma_f32_16x16x32_bf16 v[16:19], v[210:213], v[174:177], v[16:19]
	v_mfma_f32_16x16x32_bf16 v[12:15], v[202:205], v[182:185], v[12:15]
	v_mfma_f32_16x16x32_bf16 v[8:11], v[210:213], v[182:185], v[8:11]
	v_mfma_f32_16x16x32_bf16 v[4:7], v[202:205], v[190:193], v[4:7]
	v_mfma_f32_16x16x32_bf16 v[0:3], v[210:213], v[190:193], v[0:3]
	v_mfma_f32_16x16x32_bf16 v[28:31], v[206:209], v[170:173], v[28:31]
	v_mfma_f32_16x16x32_bf16 v[24:27], v[214:217], v[170:173], v[24:27]
	v_mfma_f32_16x16x32_bf16 v[20:23], v[206:209], v[178:181], v[20:23]
	v_mfma_f32_16x16x32_bf16 v[16:19], v[214:217], v[178:181], v[16:19]
	v_mfma_f32_16x16x32_bf16 v[12:15], v[206:209], v[186:189], v[12:15]
	v_mfma_f32_16x16x32_bf16 v[8:11], v[214:217], v[186:189], v[8:11]
	v_mfma_f32_16x16x32_bf16 v[4:7], v[206:209], v[198:201], v[4:7]
	v_mfma_f32_16x16x32_bf16 v[0:3], v[214:217], v[198:201], v[0:3]
	s_add_i32 s65, 0, 0x18000
	v_add_u32_e32 v162, s65, v145
	s_barrier
; #define PG8_STAGE(bufoff, gbase, voff) do { _Pragma("unroll") for (int _i = 0; _i < 2; ++_i) \
;         __builtin_amdgcn_global_load_lds((const unsigned*)((const char*)(gbase) + (voff)[_i]), (LAS unsigned*)(lds + (bufoff) + ldsw + _i * 8192), 16, 0, 0); } while (0)
; #define PG8_LDA(dst, b, h) do { _Pragma("unroll") for (int m = 0; m < 4; ++m) _Pragma("unroll") for (int k = 0; k < 2; ++k) dst[m][k] = *(const LAS bf16x8*)(lds + PG8_SA(b, h) + aoff + m * 2048 + k * 1024); } while (0)
; #define PG8_LDB(dst, b, h) do { _Pragma("unroll") for (int n = 0; n < 2; ++n) _Pragma("unroll") for (int k = 0; k < 2; ++k) dst[n][k] = *(const LAS bf16x8*)(lds + PG8_SB(b, h) + boff + n * 2048 + k * 1024); } while (0)
; #define PG8_MMA(ai, bj, At, Bt) do { __builtin_amdgcn_s_setprio(1); _Pragma("unroll") for (int m = 0; m < 4; ++m) _Pragma("unroll") for (int n = 0; n < 2; ++n) _Pragma("unroll") for (int k = 0; k < 2; ++k) \
;         acc[ai][bj][m][n] = __builtin_amdgcn_mfma_f32_16x16x32_bf16(Bt[n][k], At[m][k], acc[ai][bj][m][n], 0, 0, 0); __builtin_amdgcn_s_setprio(0); } while (0)
; #define PG8_WAIT_V(n) asm volatile("s_waitcnt vmcnt(" #n ")" ::: "memory")
; #define PG8_WAIT_L(n) asm volatile("s_waitcnt lgkmcnt(" #n ")" ::: "memory")
; #define PG8_BAR __builtin_amdgcn_s_barrier()
; #define PG8_SCHED __builtin_amdgcn_sched_barrier(0)
; template <class Epi, class Sched>
; __device__ __forceinline__ void gemm_phase(LAS unsigned char* lds, const Gemm g, const Sched& S, const Epi& E) {
;     ...
;             PG8_WAIT_V(6); PG8_BAR; PG8_MMA(1, 1, At, B1); PG8_BAR;
;             PG8_LDB(B0, 1, 0); PG8_SCHED; PG8_LDA(At, 1, 0); PG8_STAGE(PG8_SA(0, 1), a2 + hstepA, voffA);
;             PG8_WAIT_L(8); PG8_BAR; PG8_WAIT_L(0); PG8_MMA(0, 0, At, B0); PG8_BAR; PG8_SCHED;
;             PG8_LDB(B1, 1, 1); PG8_STAGE(PG8_SB(1, 0), b3, voffB);
;             PG8_BAR; PG8_WAIT_L(0); PG8_MMA(0, 1, At, B1); PG8_BAR;
;             PG8_LDA(At, 1, 1); PG8_STAGE(PG8_SA(1, 0), a3, voffA);
;             PG8_BAR; PG8_WAIT_L(0); PG8_MMA(1, 0, At, B0); PG8_BAR; PG8_SCHED;
;             PG8_STAGE(PG8_SB(1, 1), b3 + hstepB, voffB);
	ds_read_b128 v[150:153], v162
	ds_read_b128 v[154:157], v162 offset:1024
	ds_read_b128 v[158:161], v162 offset:2048
	ds_read_b128 v[162:165], v162 offset:3072
	s_add_u32 s26, s26, 0x80000
	s_addc_u32 s27, s27, 0
	s_mov_b32 m0, s29
	v_lshl_add_u64 v[202:203], s[26:27], 0, v[128:129]
	ds_read_b128 v[166:169], v148 offset:32768
	ds_read_b128 v[170:173], v148 offset:33792
	ds_read_b128 v[174:177], v148 offset:34816
	ds_read_b128 v[178:181], v148 offset:35840
	ds_read_b128 v[182:185], v148 offset:36864
	ds_read_b128 v[186:189], v148 offset:37888
	ds_read_b128 v[190:193], v148 offset:38912
	ds_read_b128 v[198:201], v148 offset:39936
	global_load_lds_dwordx4 v[202:203], off
	v_lshl_add_u64 v[202:203], s[26:27], 0, v[132:133]
	s_mov_b32 m0, s30
	s_nop 0
	global_load_lds_dwordx4 v[202:203], off
	s_waitcnt lgkmcnt(8)
	s_barrier
	s_waitcnt lgkmcnt(0)
	s_waitcnt lgkmcnt(0)
	v_mfma_f32_16x16x32_bf16 v[124:127], v[150:153], v[166:169], v[124:127]
	v_mfma_f32_16x16x32_bf16 v[120:123], v[158:161], v[166:169], v[120:123]
	v_mfma_f32_16x16x32_bf16 v[116:119], v[150:153], v[174:177], v[116:119]
	v_mfma_f32_16x16x32_bf16 v[112:115], v[158:161], v[174:177], v[112:115]
	v_mfma_f32_16x16x32_bf16 v[108:111], v[150:153], v[182:185], v[108:111]
	v_mfma_f32_16x16x32_bf16 v[104:107], v[158:161], v[182:185], v[104:107]
	v_mfma_f32_16x16x32_bf16 v[100:103], v[150:153], v[190:193], v[100:103]
	v_mfma_f32_16x16x32_bf16 v[96:99], v[158:161], v[190:193], v[96:99]
	v_mfma_f32_16x16x32_bf16 v[124:127], v[154:157], v[170:173], v[124:127]
	v_mfma_f32_16x16x32_bf16 v[120:123], v[162:165], v[170:173], v[120:123]
	v_mfma_f32_16x16x32_bf16 v[116:119], v[154:157], v[178:181], v[116:119]
	v_mfma_f32_16x16x32_bf16 v[112:115], v[162:165], v[178:181], v[112:115]
	v_mfma_f32_16x16x32_bf16 v[108:111], v[154:157], v[186:189], v[108:111]
	v_mfma_f32_16x16x32_bf16 v[104:107], v[162:165], v[186:189], v[104:107]
	v_mfma_f32_16x16x32_bf16 v[100:103], v[154:157], v[198:201], v[100:103]
	v_mfma_f32_16x16x32_bf16 v[96:99], v[162:165], v[198:201], v[96:99]
	s_barrier
	s_add_i32 s26, 0, 0x1c000
	s_add_i32 s27, s65, s22
	v_add_u32_e32 v197, s26, v145
	v_lshl_add_u64 v[194:195], v[194:195], 0, s[8:9]
	s_mov_b32 m0, s27
	ds_read_b128 v[202:205], v197
	ds_read_b128 v[206:209], v197 offset:1024
	ds_read_b128 v[210:213], v197 offset:2048
	ds_read_b128 v[214:217], v197 offset:3072
	global_load_lds_dwordx4 v[194:195], off
	v_lshl_add_u64 v[194:195], v[218:219], 0, s[8:9]
	s_add_i32 m0, s27, 0x2000
	s_nop 0
	global_load_lds_dwordx4 v[194:195], off
	s_barrier
	s_waitcnt lgkmcnt(0)
	s_waitcnt lgkmcnt(0)
	v_mfma_f32_16x16x32_bf16 v[76:79], v[202:205], v[166:169], v[76:79]
	v_mfma_f32_16x16x32_bf16 v[68:71], v[210:213], v[166:169], v[68:71]
	v_mfma_f32_16x16x32_bf16 v[60:63], v[202:205], v[174:177], v[60:63]
	v_mfma_f32_16x16x32_bf16 v[56:59], v[210:213], v[174:177], v[56:59]
	v_mfma_f32_16x16x32_bf16 v[44:47], v[202:205], v[182:185], v[44:47]
	v_mfma_f32_16x16x32_bf16 v[40:43], v[210:213], v[182:185], v[40:43]
	v_mfma_f32_16x16x32_bf16 v[36:39], v[202:205], v[190:193], v[36:39]
	v_mfma_f32_16x16x32_bf16 v[32:35], v[210:213], v[190:193], v[32:35]
	v_mfma_f32_16x16x32_bf16 v[76:79], v[206:209], v[170:173], v[76:79]
	v_mfma_f32_16x16x32_bf16 v[68:71], v[214:217], v[170:173], v[68:71]
	v_mfma_f32_16x16x32_bf16 v[60:63], v[206:209], v[178:181], v[60:63]
	v_mfma_f32_16x16x32_bf16 v[56:59], v[214:217], v[178:181], v[56:59]
	v_mfma_f32_16x16x32_bf16 v[44:47], v[206:209], v[186:189], v[44:47]
	v_mfma_f32_16x16x32_bf16 v[40:43], v[214:217], v[186:189], v[40:43]
	v_mfma_f32_16x16x32_bf16 v[36:39], v[206:209], v[198:201], v[36:39]
	v_mfma_f32_16x16x32_bf16 v[32:35], v[214:217], v[198:201], v[32:35]
	s_mov_b32 m0, s33
	v_lshl_add_u64 v[194:195], v[220:221], 0, s[8:9]
	s_barrier
	ds_read_b128 v[166:169], v148 offset:49152
	ds_read_b128 v[170:173], v148 offset:50176
	ds_read_b128 v[174:177], v148 offset:51200
	ds_read_b128 v[178:181], v148 offset:52224
	ds_read_b128 v[182:185], v148 offset:53248
	ds_read_b128 v[186:189], v148 offset:54272
	ds_read_b128 v[190:193], v148 offset:55296
	ds_read_b128 v[198:201], v148 offset:56320
	global_load_lds_dwordx4 v[194:195], off
	v_lshl_add_u64 v[194:195], v[222:223], 0, s[8:9]
	s_mov_b32 m0, s34
	s_nop 0
	global_load_lds_dwordx4 v[194:195], off
	s_barrier
	s_waitcnt lgkmcnt(0)
	s_waitcnt lgkmcnt(0)
	v_mfma_f32_16x16x32_bf16 v[92:95], v[150:153], v[166:169], v[92:95]
	v_mfma_f32_16x16x32_bf16 v[88:91], v[158:161], v[166:169], v[88:91]
	v_mfma_f32_16x16x32_bf16 v[84:87], v[150:153], v[174:177], v[84:87]
	v_mfma_f32_16x16x32_bf16 v[80:83], v[158:161], v[174:177], v[80:83]
	v_mfma_f32_16x16x32_bf16 v[72:75], v[150:153], v[182:185], v[72:75]
	v_mfma_f32_16x16x32_bf16 v[64:67], v[158:161], v[182:185], v[64:67]
	v_mfma_f32_16x16x32_bf16 v[52:55], v[150:153], v[190:193], v[52:55]
	v_mfma_f32_16x16x32_bf16 v[48:51], v[158:161], v[190:193], v[48:51]
	v_mfma_f32_16x16x32_bf16 v[92:95], v[154:157], v[170:173], v[92:95]
	v_mfma_f32_16x16x32_bf16 v[88:91], v[162:165], v[170:173], v[88:91]
	v_mfma_f32_16x16x32_bf16 v[84:87], v[154:157], v[178:181], v[84:87]
	v_mfma_f32_16x16x32_bf16 v[80:83], v[162:165], v[178:181], v[80:83]
	v_mfma_f32_16x16x32_bf16 v[72:75], v[154:157], v[186:189], v[72:75]
	v_mfma_f32_16x16x32_bf16 v[64:67], v[162:165], v[186:189], v[64:67]
	v_mfma_f32_16x16x32_bf16 v[52:55], v[154:157], v[198:201], v[52:55]
	v_mfma_f32_16x16x32_bf16 v[48:51], v[162:165], v[198:201], v[48:51]
	s_barrier
	s_add_u32 s24, s24, 0x80080
	s_addc_u32 s25, s25, 0
	s_add_i32 s26, s26, s22
	v_lshl_add_u64 v[150:151], s[24:25], 0, v[130:131]
	s_mov_b32 m0, s26
	s_nop 0
	global_load_lds_dwordx4 v[150:151], off
	v_lshl_add_u64 v[150:151], s[24:25], 0, v[134:135]
	s_add_i32 m0, s26, 0x2000
	s_nop 0
	global_load_lds_dwordx4 v[150:151], off
	s_waitcnt vmcnt(6)
	s_barrier
; __device__ __forceinline__ unsigned pk_bf16(float lo, float hi) { unsigned r; asm volatile("v_cvt_pk_bf16_f32 %0, %1, %2" : "=v"(r) : "v"(lo), "v"(hi)); return r; }
; __device__ __forceinline__ float sigmoidf_(float x) { return __builtin_amdgcn_rcpf(1.0f + __expf(-x)); }
; #define PG8_MMA(ai, bj, At, Bt) do { __builtin_amdgcn_s_setprio(1); _Pragma("unroll") for (int m = 0; m < 4; ++m) _Pragma("unroll") for (int n = 0; n < 2; ++n) _Pragma("unroll") for (int k = 0; k < 2; ++k) \
;         acc[ai][bj][m][n] = __builtin_amdgcn_mfma_f32_16x16x32_bf16(Bt[n][k], At[m][k], acc[ai][bj][m][n], 0, 0, 0); __builtin_amdgcn_s_setprio(0); } while (0)
; #define PG8_WAIT_V(n) asm volatile("s_waitcnt vmcnt(" #n ")" ::: "memory")
; template <class Epi, class Sched>
; __device__ __forceinline__ void gemm_phase(LAS unsigned char* lds, const Gemm g, const Sched& S, const Epi& E) {
;     ...
;             PG8_WAIT_V(6); PG8_BAR; PG8_MMA(1, 1, At, B1); PG8_BAR;
;         }
;         if constexpr (!Epi::AFTER_DRAIN) E(acc, cur, wr, wc, fr, fq);
;         if (!has_next) break;
;     __device__ __forceinline__ void operator()(const f32x4 (&acc)[2][2][4][2], const Unit& u, int wr, int wc, int fr, int fq) const {
;         const int row0 = u.pm * 256 + wr * 64 + fr, col0 = coff + u.pn * 256 + wc * 32 + 8 * fq;
; #pragma unroll
;         for (int bj = 0; bj < 2; ++bj) {
;             const int c = col0 + bj * 128;
;             f32x4 s0, s1;
;             if (MODE == 0) { s0 = vec ? *(const f32x4*)(vec + c) : (f32x4){1.f, 1.f, 1.f, 1.f}; s1 = vec ? *(const f32x4*)(vec + c + 4) : (f32x4){1.f, 1.f, 1.f, 1.f}; }
;             else { s0 = *(const f32x4*)(vec + c); s1 = *(const f32x4*)(vec + c + 4); }
; #pragma unroll
;             for (int ai = 0; ai < 2; ++ai)
; #pragma unroll
;                 for (int m = 0; m < 4; ++m) {
;                     f32x4 v0 = acc[ai][bj][m][0], v1 = acc[ai][bj][m][1];
;                     if (MODE == 0) { v0 = v0 * s0; v1 = v1 * s1; }
;                     else {
; #pragma unroll
;                         for (int j = 0; j < 4; ++j) { v0[j] = sigmoidf_(v0[j] + s0[j]); v1[j] = sigmoidf_(v1[j] + s1[j]); } }
;                     u32x4 w; w.x = pk_bf16(v0[0], v0[1]); w.y = pk_bf16(v0[2], v0[3]); w.z = pk_bf16(v1[0], v1[1]); w.w = pk_bf16(v1[2], v1[3]);
;                     *(u32x4*)(O + (size_t)(row0 + ai * 128 + m * 16) * ldc + c) = w;
;                 }
	v_mfma_f32_16x16x32_bf16 v[28:31], v[202:205], v[166:169], v[28:31]
	v_mfma_f32_16x16x32_bf16 v[24:27], v[210:213], v[166:169], v[24:27]
	v_mfma_f32_16x16x32_bf16 v[20:23], v[202:205], v[174:177], v[20:23]
	v_mfma_f32_16x16x32_bf16 v[16:19], v[210:213], v[174:177], v[16:19]
	v_mfma_f32_16x16x32_bf16 v[12:15], v[202:205], v[182:185], v[12:15]
	v_mfma_f32_16x16x32_bf16 v[8:11], v[210:213], v[182:185], v[8:11]
	v_mfma_f32_16x16x32_bf16 v[4:7], v[202:205], v[190:193], v[4:7]
	v_mfma_f32_16x16x32_bf16 v[0:3], v[210:213], v[190:193], v[0:3]
	v_mfma_f32_16x16x32_bf16 v[28:31], v[206:209], v[170:173], v[28:31]
	v_mfma_f32_16x16x32_bf16 v[24:27], v[214:217], v[170:173], v[24:27]
	v_mfma_f32_16x16x32_bf16 v[20:23], v[206:209], v[178:181], v[20:23]
	v_mfma_f32_16x16x32_bf16 v[16:19], v[214:217], v[178:181], v[16:19]
	v_mfma_f32_16x16x32_bf16 v[12:15], v[206:209], v[186:189], v[12:15]
	v_mfma_f32_16x16x32_bf16 v[8:11], v[214:217], v[186:189], v[8:11]
	v_mfma_f32_16x16x32_bf16 v[4:7], v[206:209], v[198:201], v[4:7]
	v_mfma_f32_16x16x32_bf16 v[0:3], v[214:217], v[198:201], v[0:3]
	s_add_i32 s64, s64, 2
	s_add_u32 s20, s20, 0x100
	s_addc_u32 s21, s21, 0
	s_add_u32 s62, s62, 0x100
	s_addc_u32 s63, s63, 0
	s_cmp_gt_u32 s64, 29
	s_barrier
	s_cbranch_scc0 .LBB0_121
	s_setprio 0
	s_nop 0
	s_nop 0
	s_nop 0
	s_nop 0
	s_nop 0
	s_nop 0
	s_nop 0
	s_nop 0
	s_nop 0
	s_nop 0
	s_nop 0
	s_nop 0
	s_nop 0
	s_nop 0
	s_nop 0
	v_lshl_or_b32 v150, s59, 8, v146
	v_lshl_add_u32 v152, s16, 8, v144
	v_ashrrev_i32_e32 v151, 31, v150
	v_cvt_pk_bf16_f32 v124, v124, v125
	v_cvt_pk_bf16_f32 v125, v126, v127
	v_cvt_pk_bf16_f32 v126, v120, v121
	v_mov_b64_e32 v[120:121], s[48:49]
	v_cvt_pk_bf16_f32 v127, v122, v123
	v_mad_i64_i32 v[122:123], s[4:5], v152, s58, v[120:121]
	v_lshlrev_b64 v[150:151], 1, v[150:151]
	v_lshl_add_u64 v[122:123], v[122:123], 0, v[150:151]
	global_store_dwordx4 v[122:123], v[124:127], off
	v_cvt_pk_bf16_f32 v116, v116, v117
	v_cvt_pk_bf16_f32 v117, v118, v119
	v_cvt_pk_bf16_f32 v118, v112, v113
	v_or_b32_e32 v112, 16, v152
	v_mad_i64_i32 v[112:113], s[4:5], v112, s58, v[120:121]
	v_lshl_add_u64 v[112:113], v[112:113], 0, v[150:151]
	v_cvt_pk_bf16_f32 v119, v114, v115
	global_store_dwordx4 v[112:113], v[116:119], off
	v_cvt_pk_bf16_f32 v108, v108, v109
	v_cvt_pk_bf16_f32 v109, v110, v111
	v_cvt_pk_bf16_f32 v110, v104, v105
	v_or_b32_e32 v104, 32, v152
	v_mad_i64_i32 v[104:105], s[4:5], v104, s58, v[120:121]
	v_lshl_add_u64 v[104:105], v[104:105], 0, v[150:151]
	v_cvt_pk_bf16_f32 v111, v106, v107
	global_store_dwordx4 v[104:105], v[108:111], off
	v_cvt_pk_bf16_f32 v100, v100, v101
	v_cvt_pk_bf16_f32 v101, v102, v103
	v_cvt_pk_bf16_f32 v102, v96, v97
	v_or_b32_e32 v96, 48, v152
	v_mad_i64_i32 v[96:97], s[4:5], v96, s58, v[120:121]
	v_cvt_pk_bf16_f32 v103, v98, v99
	v_lshl_add_u64 v[96:97], v[96:97], 0, v[150:151]
	v_add_u32_e32 v98, 0x80, v152
	global_store_dwordx4 v[96:97], v[100:103], off
	v_cvt_pk_bf16_f32 v92, v92, v93
	v_cvt_pk_bf16_f32 v93, v94, v95
	v_cvt_pk_bf16_f32 v94, v88, v89
	v_mad_i64_i32 v[88:89], s[4:5], v98, s58, v[120:121]
	v_lshl_add_u64 v[88:89], v[88:89], 0, v[150:151]
	v_cvt_pk_bf16_f32 v95, v90, v91
	global_store_dwordx4 v[88:89], v[92:95], off
	v_cvt_pk_bf16_f32 v84, v84, v85
	v_cvt_pk_bf16_f32 v85, v86, v87
	v_cvt_pk_bf16_f32 v86, v80, v81
	v_add_u32_e32 v80, 0x90, v152
	v_mad_i64_i32 v[80:81], s[4:5], v80, s58, v[120:121]
	v_lshl_add_u64 v[80:81], v[80:81], 0, v[150:151]
	v_cvt_pk_bf16_f32 v87, v82, v83
	global_store_dwordx4 v[80:81], v[84:87], off
	v_cvt_pk_bf16_f32 v72, v72, v73
	v_cvt_pk_bf16_f32 v73, v74, v75
	v_cvt_pk_bf16_f32 v74, v64, v65
	v_add_u32_e32 v64, 0xa0, v152
	v_mad_i64_i32 v[64:65], s[4:5], v64, s58, v[120:121]
	v_lshl_add_u64 v[64:65], v[64:65], 0, v[150:151]
	v_cvt_pk_bf16_f32 v75, v66, v67
	global_store_dwordx4 v[64:65], v[72:75], off
	v_cvt_pk_bf16_f32 v52, v52, v53
	v_cvt_pk_bf16_f32 v53, v54, v55
	v_cvt_pk_bf16_f32 v54, v48, v49
	v_add_u32_e32 v48, 0xb0, v152
	v_mad_i64_i32 v[48:49], s[4:5], v48, s58, v[120:121]
	v_lshl_add_u64 v[66:67], v[48:49], 0, v[150:151]
	v_cvt_pk_bf16_f32 v55, v50, v51
	global_store_dwordx4 v[66:67], v[52:55], off
	v_cvt_pk_bf16_f32 v48, v76, v77
	v_cvt_pk_bf16_f32 v49, v78, v79
	v_cvt_pk_bf16_f32 v50, v68, v69
	v_cvt_pk_bf16_f32 v51, v70, v71
	s_and_b64 vcc, exec, s[6:7]
	s_mov_b32 s59, s10
	s_mov_b32 s16, s12
	s_mov_b64 s[24:25], s[18:19]
	s_mov_b64 s[20:21], s[14:15]
	global_store_dwordx4 v[122:123], v[48:51], off offset:256
	s_nop 1
	v_cvt_pk_bf16_f32 v48, v60, v61
	v_cvt_pk_bf16_f32 v49, v62, v63
	v_cvt_pk_bf16_f32 v50, v56, v57
	v_cvt_pk_bf16_f32 v51, v58, v59
	global_store_dwordx4 v[112:113], v[48:51], off offset:256
	v_cvt_pk_bf16_f32 v44, v44, v45
	v_cvt_pk_bf16_f32 v45, v46, v47
	v_cvt_pk_bf16_f32 v46, v40, v41
	v_cvt_pk_bf16_f32 v47, v42, v43
	global_store_dwordx4 v[104:105], v[44:47], off offset:256
	v_cvt_pk_bf16_f32 v36, v36, v37
	v_cvt_pk_bf16_f32 v37, v38, v39
	v_cvt_pk_bf16_f32 v38, v32, v33
	v_cvt_pk_bf16_f32 v39, v34, v35
	global_store_dwordx4 v[96:97], v[36:39], off offset:256
	v_cvt_pk_bf16_f32 v28, v28, v29
	v_cvt_pk_bf16_f32 v29, v30, v31
	v_cvt_pk_bf16_f32 v30, v24, v25
	v_cvt_pk_bf16_f32 v31, v26, v27
	global_store_dwordx4 v[88:89], v[28:31], off offset:256
	v_cvt_pk_bf16_f32 v20, v20, v21
	v_cvt_pk_bf16_f32 v21, v22, v23
	v_cvt_pk_bf16_f32 v22, v16, v17
	v_cvt_pk_bf16_f32 v23, v18, v19
	global_store_dwordx4 v[80:81], v[20:23], off offset:256
	v_cvt_pk_bf16_f32 v12, v12, v13
	v_cvt_pk_bf16_f32 v13, v14, v15
	v_cvt_pk_bf16_f32 v14, v8, v9
	v_cvt_pk_bf16_f32 v15, v10, v11
	global_store_dwordx4 v[64:65], v[12:15], off offset:256
	v_cvt_pk_bf16_f32 v4, v4, v5
	v_cvt_pk_bf16_f32 v5, v6, v7
	v_cvt_pk_bf16_f32 v6, v0, v1
	v_cvt_pk_bf16_f32 v7, v2, v3
	global_store_dwordx4 v[66:67], v[4:7], off offset:256
	s_cbranch_vccz .LBB0_114
	s_waitcnt vmcnt(0)
	s_cmpk_gt_u32 s0, 0xff
	s_cbranch_scc1 .LBB0_125
	s_barrier
